# phase 12 hipcc K-loop: s_setprio 1 around each K-step's MFMA segment (the loop had no priority flips)
# baseline (speedup 1.0000x reference)
.LBB0_917:
	s_add_u32 s100, s0, s98
	s_add_u32 s100, s100, 0x80
	s_and_b32 s100, s100, 0xfff
	s_sub_u32 s100, s100, 0x80
	s_subb_u32 s101, 0, 0
	s_and_b32 s8, s7, 0x2000
	s_xor_b32 s9, s8, 0x2000
	s_lshl_b32 s8, s8, 1
	v_lshl_add_u32 v117, s9, 1, v114
	v_add_u32_e32 v142, s8, v113
	v_or_b32_e32 v143, s8, v64
	v_readfirstlane_b32 s8, v117
	v_add_u32_e32 v134, 0x8000, v117
	v_lshl_add_u64 v[118:119], v[82:83], 0, s[100:101]
	v_add_u32_e32 v135, 0x1000, v117
	v_readfirstlane_b32 s9, v134
	s_mov_b32 m0, s8
	s_waitcnt vmcnt(0)
	s_waitcnt vmcnt(0) lgkmcnt(0)
	s_barrier
	v_lshl_add_u64 v[120:121], v[84:85], 0, s[100:101]
	v_add_u32_e32 v136, 0x9000, v117
	v_readfirstlane_b32 s10, v135
	global_load_lds_dwordx4 v[118:119], off
	s_mov_b32 m0, s9
	v_lshl_add_u64 v[122:123], v[86:87], 0, s[100:101]
	v_add_u32_e32 v137, 0x2000, v117
	v_readfirstlane_b32 s11, v136
	global_load_lds_dwordx4 v[120:121], off
	s_mov_b32 m0, s10
	v_lshl_add_u64 v[124:125], v[88:89], 0, s[100:101]
	v_add_u32_e32 v138, 0xa000, v117
	v_readfirstlane_b32 s12, v137
	global_load_lds_dwordx4 v[122:123], off
	s_mov_b32 m0, s11
	v_lshl_add_u64 v[126:127], v[90:91], 0, s[100:101]
	v_add_u32_e32 v139, 0x3000, v117
	v_readfirstlane_b32 s13, v138
	global_load_lds_dwordx4 v[124:125], off
	s_mov_b32 m0, s12
	v_lshl_add_u64 v[128:129], v[92:93], 0, s[100:101]
	v_add_u32_e32 v117, 0xb000, v117
	v_readfirstlane_b32 s14, v139
	global_load_lds_dwordx4 v[126:127], off
	s_mov_b32 m0, s13
	v_lshl_add_u64 v[130:131], v[94:95], 0, s[100:101]
	v_readfirstlane_b32 s15, v117
	global_load_lds_dwordx4 v[128:129], off
	s_mov_b32 m0, s14
	v_lshl_add_u64 v[132:133], v[96:97], 0, s[100:101]
	global_load_lds_dwordx4 v[130:131], off
	s_mov_b32 m0, s15
	v_add_u32_e32 v140, v143, v116
	global_load_lds_dwordx4 v[132:133], off
	v_add_u32_e32 v144, v142, v116
	ds_read_b128 v[118:121], v140 offset:32768
	ds_read_b128 v[122:125], v140 offset:34816
	ds_read_b128 v[126:129], v144
	ds_read_b128 v[130:133], v144 offset:2048
	ds_read_b128 v[134:137], v140 offset:36864
	ds_read_b128 v[138:141], v140 offset:38912
	s_waitcnt lgkmcnt(0)
	s_setprio 1
	v_mfma_f32_16x16x32_bf16 v[60:63], v[118:121], v[126:129], v[60:63]
	v_add_u32_e32 v117, v142, v115
	v_add_u32_e32 v142, v143, v115
	s_add_u32 s0, s0, 0x80
	v_mfma_f32_16x16x32_bf16 v[56:59], v[122:125], v[126:129], v[56:59]
	s_addc_u32 s1, s1, 0
	s_addk_i32 s7, 0x2000
	s_cmpk_eq_i32 s0, 0xf80
	v_mfma_f32_16x16x32_bf16 v[52:55], v[134:137], v[126:129], v[52:55]
	v_mfma_f32_16x16x32_bf16 v[48:51], v[138:141], v[126:129], v[48:51]
	v_mfma_f32_16x16x32_bf16 v[44:47], v[118:121], v[130:133], v[44:47]
	v_mfma_f32_16x16x32_bf16 v[40:43], v[122:125], v[130:133], v[40:43]
	v_mfma_f32_16x16x32_bf16 v[36:39], v[134:137], v[130:133], v[36:39]
	v_mfma_f32_16x16x32_bf16 v[32:35], v[138:141], v[130:133], v[32:35]
	ds_read_b128 v[126:129], v144 offset:4096
	ds_read_b128 v[130:133], v144 offset:6144
	s_waitcnt lgkmcnt(0)
	v_mfma_f32_16x16x32_bf16 v[28:31], v[118:121], v[126:129], v[28:31]
	v_mfma_f32_16x16x32_bf16 v[24:27], v[122:125], v[126:129], v[24:27]
	v_mfma_f32_16x16x32_bf16 v[20:23], v[134:137], v[126:129], v[20:23]
	v_mfma_f32_16x16x32_bf16 v[16:19], v[138:141], v[126:129], v[16:19]
	v_mfma_f32_16x16x32_bf16 v[8:11], v[118:121], v[130:133], v[8:11]
	v_mfma_f32_16x16x32_bf16 v[4:7], v[122:125], v[130:133], v[4:7]
	ds_read_b128 v[118:121], v142 offset:32768
	ds_read_b128 v[122:125], v142 offset:34816
	v_mfma_f32_16x16x32_bf16 v[0:3], v[134:137], v[130:133], v[0:3]
	v_mfma_f32_16x16x32_bf16 v[12:15], v[138:141], v[130:133], v[12:15]
	ds_read_b128 v[126:129], v117
	ds_read_b128 v[130:133], v117 offset:2048
	ds_read_b128 v[134:137], v142 offset:36864
	ds_read_b128 v[138:141], v142 offset:38912
	s_waitcnt lgkmcnt(0)
	v_mfma_f32_16x16x32_bf16 v[60:63], v[118:121], v[126:129], v[60:63]
	v_mfma_f32_16x16x32_bf16 v[56:59], v[122:125], v[126:129], v[56:59]
	v_mfma_f32_16x16x32_bf16 v[52:55], v[134:137], v[126:129], v[52:55]
	v_mfma_f32_16x16x32_bf16 v[48:51], v[138:141], v[126:129], v[48:51]
	v_mfma_f32_16x16x32_bf16 v[44:47], v[118:121], v[130:133], v[44:47]
	v_mfma_f32_16x16x32_bf16 v[40:43], v[122:125], v[130:133], v[40:43]
	v_mfma_f32_16x16x32_bf16 v[36:39], v[134:137], v[130:133], v[36:39]
	v_mfma_f32_16x16x32_bf16 v[32:35], v[138:141], v[130:133], v[32:35]
	ds_read_b128 v[126:129], v117 offset:4096
	ds_read_b128 v[130:133], v117 offset:6144
	s_waitcnt lgkmcnt(0)
	v_mfma_f32_16x16x32_bf16 v[28:31], v[118:121], v[126:129], v[28:31]
	v_mfma_f32_16x16x32_bf16 v[24:27], v[122:125], v[126:129], v[24:27]
	v_mfma_f32_16x16x32_bf16 v[20:23], v[134:137], v[126:129], v[20:23]
	v_mfma_f32_16x16x32_bf16 v[16:19], v[138:141], v[126:129], v[16:19]
	v_mfma_f32_16x16x32_bf16 v[8:11], v[118:121], v[130:133], v[8:11]
	v_mfma_f32_16x16x32_bf16 v[4:7], v[122:125], v[130:133], v[4:7]
	v_mfma_f32_16x16x32_bf16 v[0:3], v[134:137], v[130:133], v[0:3]
	v_mfma_f32_16x16x32_bf16 v[12:15], v[138:141], v[130:133], v[12:15]
	s_setprio 0
	s_cbranch_scc0 .LBB0_917
	v_add_u32_e32 v114, v64, v116
	s_waitcnt vmcnt(0)
	s_waitcnt vmcnt(0)
	s_barrier
	ds_read_b128 v[82:85], v114 offset:49152
	v_add_u32_e32 v124, v113, v116
	ds_read_b128 v[86:89], v114 offset:51200
	ds_read_b128 v[90:93], v124 offset:16384
	ds_read_b128 v[94:97], v124 offset:18432
	ds_read_b128 v[116:119], v114 offset:53248
	ds_read_b128 v[120:123], v114 offset:55296
	v_add_u32_e32 v113, v113, v115
	v_add_u32_e32 v64, v64, v115
	s_waitcnt lgkmcnt(3)
	s_setprio 1
	v_mfma_f32_16x16x32_bf16 v[60:63], v[82:85], v[90:93], v[60:63]
	s_ashr_i32 s37, s36, 31
	s_lshl_b64 s[0:1], s[36:37], 17
	s_add_u32 s0, s2, s0
	v_mfma_f32_16x16x32_bf16 v[56:59], v[86:89], v[90:93], v[56:59]
	s_addc_u32 s1, s3, s1
	v_lshl_add_u64 v[114:115], s[0:1], 0, v[68:69]
	s_add_i32 s40, s40, s96
	s_waitcnt lgkmcnt(1)
	v_mfma_f32_16x16x32_bf16 v[52:55], v[116:119], v[90:93], v[52:55]
	v_cmp_ge_i32_e32 vcc, s40, v98
	s_and_b64 vcc, exec, vcc
	s_add_i32 s33, s33, s38
	s_waitcnt lgkmcnt(0)
	v_mfma_f32_16x16x32_bf16 v[48:51], v[120:123], v[90:93], v[48:51]
	ds_read_b128 v[90:93], v124 offset:20480
	ds_read_b128 v[124:127], v124 offset:22528
	ds_read_b128 v[128:131], v113 offset:16384
	ds_read_b128 v[132:135], v113 offset:18432
	ds_read_b128 v[136:139], v113 offset:20480
	ds_read_b128 v[140:143], v113 offset:22528
	ds_read_b128 v[144:147], v64 offset:49152
	ds_read_b128 v[148:151], v64 offset:51200
	s_waitcnt lgkmcnt(1)
	v_mfma_f32_16x16x32_bf16 v[60:63], v[144:147], v[128:131], v[60:63]
	v_mfma_f32_16x16x32_bf16 v[44:47], v[82:85], v[94:97], v[44:47]
	s_nop 6
	v_mul_f32_e32 v113, 0xbfb8aa3b, v61
	v_exp_f32_e32 v113, v113
	v_mfma_f32_16x16x32_bf16 v[40:43], v[86:89], v[94:97], v[40:43]
	v_mfma_f32_16x16x32_bf16 v[36:39], v[116:119], v[94:97], v[36:39]
	v_mfma_f32_16x16x32_bf16 v[32:35], v[120:123], v[94:97], v[32:35]
	ds_read_b128 v[94:97], v64 offset:53248
	ds_read_b128 v[152:155], v64 offset:55296
	v_mul_f32_e32 v64, 0xbfb8aa3b, v60
	v_exp_f32_e32 v64, v64
	v_mfma_f32_16x16x32_bf16 v[28:31], v[82:85], v[90:93], v[28:31]
	v_add_f32_e32 v64, 1.0, v64
	v_rcp_f32_e32 v156, v64
	v_add_f32_e32 v64, 1.0, v113
	v_rcp_f32_e32 v157, v64
	v_mul_f32_e32 v64, 0xbfb8aa3b, v62
	v_mfma_f32_16x16x32_bf16 v[24:27], v[86:89], v[90:93], v[24:27]
	v_exp_f32_e32 v64, v64
	v_pk_mul_f32 v[60:61], v[60:61], v[156:157]
	v_add_f32_e32 v64, 1.0, v64
	v_mfma_f32_16x16x32_bf16 v[20:23], v[116:119], v[90:93], v[20:23]
	v_mfma_f32_16x16x32_bf16 v[16:19], v[120:123], v[90:93], v[16:19]
	v_mul_f32_e32 v90, 0xbfb8aa3b, v63
	v_exp_f32_e32 v90, v90
	v_mfma_f32_16x16x32_bf16 v[8:11], v[82:85], v[124:127], v[8:11]
	v_rcp_f32_e32 v82, v64
	v_add_f32_e32 v64, 1.0, v90
	v_rcp_f32_e32 v83, v64
	s_waitcnt lgkmcnt(2)
	v_mfma_f32_16x16x32_bf16 v[56:59], v[148:151], v[128:131], v[56:59]
	s_waitcnt lgkmcnt(1)
	v_mfma_f32_16x16x32_bf16 v[52:55], v[94:97], v[128:131], v[52:55]
	s_waitcnt lgkmcnt(0)
	v_mfma_f32_16x16x32_bf16 v[48:51], v[152:155], v[128:131], v[48:51]
	s_nop 3
	v_mul_f32_e64 v56, v56, v60
	v_mul_f32_e64 v57, v57, v61
	v_pk_mul_f32 v[60:61], v[62:63], v[82:83]
	v_cvt_pk_bf16_f32 v56, v56, v57
	v_pk_mul_f32 v[58:59], v[58:59], v[60:61]
	v_or_b32_e32 v60, s6, v108
	v_lshlrev_b32_e32 v64, 1, v60
	v_cvt_pk_bf16_f32 v57, v58, v59
	v_lshl_add_u64 v[58:59], v[114:115], 0, v[64:65]
	global_store_dwordx2 v[58:59], v[56:57], off
	v_mul_f32_e32 v56, 0xbfb8aa3b, v52
	v_mul_f32_e32 v57, 0xbfb8aa3b, v53
	v_exp_f32_e32 v56, v56
	v_exp_f32_e32 v57, v57
	v_mul_f32_e32 v60, 0xbfb8aa3b, v54
	v_mul_f32_e32 v61, 0xbfb8aa3b, v55
	v_exp_f32_e32 v60, v60
	v_exp_f32_e32 v61, v61
	v_add_f32_e32 v56, 1.0, v56
	v_add_f32_e32 v57, 1.0, v57
	v_rcp_f32_e32 v56, v56
	v_rcp_f32_e32 v57, v57
	v_add_f32_e32 v60, 1.0, v60
	v_add_f32_e32 v61, 1.0, v61
	v_rcp_f32_e32 v60, v60
	v_rcp_f32_e32 v61, v61
	v_mfma_f32_16x16x32_bf16 v[44:47], v[144:147], v[132:135], v[44:47]
	v_mul_f32_e64 v52, v52, v56
	v_mul_f32_e64 v53, v53, v57
	v_pk_mul_f32 v[48:49], v[48:49], v[52:53]
	v_pk_mul_f32 v[52:53], v[54:55], v[60:61]
	v_cvt_pk_bf16_f32 v48, v48, v49
	v_pk_mul_f32 v[50:51], v[50:51], v[52:53]
	s_nop 1
	v_mul_f32_e32 v52, 0xbfb8aa3b, v46
	v_cvt_pk_bf16_f32 v49, v50, v51
	v_mul_f32_e32 v50, 0xbfb8aa3b, v44
	v_mul_f32_e32 v51, 0xbfb8aa3b, v45
	v_exp_f32_e32 v50, v50
	v_exp_f32_e32 v51, v51
	v_mul_f32_e32 v53, 0xbfb8aa3b, v47
	v_exp_f32_e32 v52, v52
	v_exp_f32_e32 v53, v53
	v_add_f32_e32 v50, 1.0, v50
	v_add_f32_e32 v51, 1.0, v51
	v_rcp_f32_e32 v50, v50
	v_rcp_f32_e32 v51, v51
	v_add_f32_e32 v52, 1.0, v52
	v_add_f32_e32 v53, 1.0, v53
	v_mfma_f32_16x16x32_bf16 v[40:43], v[148:151], v[132:135], v[40:43]
	v_rcp_f32_e32 v52, v52
	v_rcp_f32_e32 v53, v53
	v_pk_mul_f32 v[44:45], v[44:45], v[50:51]
	v_mfma_f32_16x16x32_bf16 v[36:39], v[94:97], v[132:135], v[36:39]
	global_store_dwordx2 v[58:59], v[48:49], off offset:32
	s_nop 2
	v_pk_mul_f32 v[40:41], v[40:41], v[44:45]
	v_pk_mul_f32 v[44:45], v[46:47], v[52:53]
	v_cvt_pk_bf16_f32 v40, v40, v41
	v_pk_mul_f32 v[42:43], v[42:43], v[44:45]
	v_mul_f32_e32 v46, 0xbfb8aa3b, v38
	v_cvt_pk_bf16_f32 v41, v42, v43
	v_mul_f32_e32 v42, 0xbfb8aa3b, v36
	v_exp_f32_e32 v44, v42
	v_mul_f32_e32 v42, 0xbfb8aa3b, v37
	v_exp_f32_e32 v45, v42
	v_mul_f32_e32 v47, 0xbfb8aa3b, v39
	v_exp_f32_e32 v46, v46
	v_exp_f32_e32 v47, v47
	v_add_f32_e32 v44, 1.0, v44
	v_add_f32_e32 v45, 1.0, v45
	v_rcp_f32_e32 v44, v44
	v_rcp_f32_e32 v45, v45
	v_add_f32_e32 v46, 1.0, v46
	v_add_f32_e32 v47, 1.0, v47
	v_mfma_f32_16x16x32_bf16 v[32:35], v[152:155], v[132:135], v[32:35]
	v_rcp_f32_e32 v46, v46
	v_rcp_f32_e32 v47, v47
	v_pk_mul_f32 v[36:37], v[36:37], v[44:45]
	v_mfma_f32_16x16x32_bf16 v[28:31], v[144:147], v[136:139], v[28:31]
	v_lshl_add_u64 v[48:49], s[0:1], 0, v[70:71]
	s_nop 2
	v_pk_mul_f32 v[32:33], v[32:33], v[36:37]
	v_pk_mul_f32 v[36:37], v[38:39], v[46:47]
	v_cvt_pk_bf16_f32 v32, v32, v33
	v_pk_mul_f32 v[34:35], v[34:35], v[36:37]
	v_lshl_add_u64 v[42:43], v[48:49], 0, v[64:65]
	v_cvt_pk_bf16_f32 v33, v34, v35
	v_mul_f32_e32 v34, 0xbfb8aa3b, v28
	v_mul_f32_e32 v35, 0xbfb8aa3b, v29
	v_exp_f32_e32 v34, v34
	v_exp_f32_e32 v35, v35
	global_store_dwordx2 v[42:43], v[32:33], off offset:32
	v_mfma_f32_16x16x32_bf16 v[24:27], v[148:151], v[136:139], v[24:27]
	v_add_f32_e32 v32, 1.0, v34
	v_add_f32_e32 v33, 1.0, v35
	v_mul_f32_e32 v34, 0xbfb8aa3b, v30
	v_mul_f32_e32 v35, 0xbfb8aa3b, v31
	v_exp_f32_e32 v34, v34
	v_exp_f32_e32 v35, v35
	v_rcp_f32_e32 v32, v32
	v_rcp_f32_e32 v33, v33
	v_add_f32_e32 v34, 1.0, v34
	v_add_f32_e32 v35, 1.0, v35
	v_rcp_f32_e32 v34, v34
	v_rcp_f32_e32 v35, v35
	v_mfma_f32_16x16x32_bf16 v[20:23], v[94:97], v[136:139], v[20:23]
	v_mul_f32_e64 v28, v28, v32
	v_mul_f32_e64 v29, v29, v33
	v_lshl_add_u64 v[36:37], s[0:1], 0, v[72:73]
	v_pk_mul_f32 v[24:25], v[24:25], v[28:29]
	v_pk_mul_f32 v[28:29], v[30:31], v[34:35]
	v_cvt_pk_bf16_f32 v24, v24, v25
	v_pk_mul_f32 v[26:27], v[26:27], v[28:29]
	s_nop 0
	v_mul_f32_e32 v30, 0xbfb8aa3b, v22
	v_cvt_pk_bf16_f32 v25, v26, v27
	v_mul_f32_e32 v26, 0xbfb8aa3b, v20
	v_exp_f32_e32 v28, v26
	v_mul_f32_e32 v26, 0xbfb8aa3b, v21
	v_exp_f32_e32 v29, v26
	v_mul_f32_e32 v31, 0xbfb8aa3b, v23
	v_exp_f32_e32 v30, v30
	v_exp_f32_e32 v31, v31
	v_add_f32_e32 v28, 1.0, v28
	v_add_f32_e32 v29, 1.0, v29
	v_rcp_f32_e32 v28, v28
	v_rcp_f32_e32 v29, v29
	v_add_f32_e32 v30, 1.0, v30
	v_add_f32_e32 v31, 1.0, v31
	v_mfma_f32_16x16x32_bf16 v[16:19], v[152:155], v[136:139], v[16:19]
	v_rcp_f32_e32 v30, v30
	v_rcp_f32_e32 v31, v31
	v_pk_mul_f32 v[20:21], v[20:21], v[28:29]
	v_mfma_f32_16x16x32_bf16 v[8:11], v[144:147], v[140:143], v[8:11]
	v_lshl_add_u64 v[26:27], v[36:37], 0, v[64:65]
	s_nop 2
	v_pk_mul_f32 v[16:17], v[16:17], v[20:21]
	v_pk_mul_f32 v[20:21], v[22:23], v[30:31]
	v_cvt_pk_bf16_f32 v16, v16, v17
	v_pk_mul_f32 v[18:19], v[18:19], v[20:21]
	v_mfma_f32_16x16x32_bf16 v[4:7], v[86:89], v[124:127], v[4:7]
	v_cvt_pk_bf16_f32 v17, v18, v19
	v_mul_f32_e32 v18, 0xbfb8aa3b, v8
	v_mul_f32_e32 v19, 0xbfb8aa3b, v9
	v_exp_f32_e32 v18, v18
	v_exp_f32_e32 v19, v19
	global_store_dwordx2 v[26:27], v[16:17], off offset:32
	v_mfma_f32_16x16x32_bf16 v[0:3], v[116:119], v[124:127], v[0:3]
	v_add_f32_e32 v16, 1.0, v18
	v_add_f32_e32 v17, 1.0, v19
	v_mul_f32_e32 v18, 0xbfb8aa3b, v10
	v_mul_f32_e32 v19, 0xbfb8aa3b, v11
	v_exp_f32_e32 v18, v18
	v_exp_f32_e32 v19, v19
	v_rcp_f32_e32 v16, v16
	v_rcp_f32_e32 v17, v17
	v_add_f32_e32 v18, 1.0, v18
	v_add_f32_e32 v19, 1.0, v19
	v_mfma_f32_16x16x32_bf16 v[4:7], v[148:151], v[140:143], v[4:7]
	v_rcp_f32_e32 v18, v18
	v_rcp_f32_e32 v19, v19
	v_pk_mul_f32 v[8:9], v[8:9], v[16:17]
	v_mfma_f32_16x16x32_bf16 v[0:3], v[94:97], v[140:143], v[0:3]
	v_lshl_add_u64 v[20:21], s[0:1], 0, v[74:75]
	s_nop 2
	v_pk_mul_f32 v[4:5], v[4:5], v[8:9]
	v_pk_mul_f32 v[8:9], v[10:11], v[18:19]
	v_cvt_pk_bf16_f32 v4, v4, v5
	v_pk_mul_f32 v[6:7], v[6:7], v[8:9]
	v_mul_f32_e32 v10, 0xbfb8aa3b, v2
	v_cvt_pk_bf16_f32 v5, v6, v7
	v_mul_f32_e32 v6, 0xbfb8aa3b, v0
	v_exp_f32_e32 v8, v6
	v_mul_f32_e32 v6, 0xbfb8aa3b, v1
	v_mul_f32_e32 v11, 0xbfb8aa3b, v3
	v_exp_f32_e32 v9, v6
	v_exp_f32_e32 v10, v10
	v_exp_f32_e32 v11, v11
	v_mfma_f32_16x16x32_bf16 v[12:15], v[120:123], v[124:127], v[12:15]
	v_add_f32_e32 v8, 1.0, v8
	v_add_f32_e32 v9, 1.0, v9
	v_add_f32_e32 v10, 1.0, v10
	v_add_f32_e32 v11, 1.0, v11
	v_rcp_f32_e32 v8, v8
	v_rcp_f32_e32 v9, v9
	v_rcp_f32_e32 v10, v10
	v_rcp_f32_e32 v11, v11
	v_mfma_f32_16x16x32_bf16 v[12:15], v[152:155], v[140:143], v[12:15]
	s_setprio 0
	v_mul_f32_e64 v0, v0, v8
	v_mul_f32_e64 v1, v1, v9
	v_lshl_add_u64 v[6:7], v[20:21], 0, v[64:65]
	v_pk_mul_f32 v[2:3], v[2:3], v[10:11]
	global_store_dwordx2 v[42:43], v[40:41], off
	global_store_dwordx2 v[26:27], v[24:25], off
	s_nop 1
	v_pk_mul_f32 v[0:1], v[12:13], v[0:1]
	v_pk_mul_f32 v[2:3], v[14:15], v[2:3]
	v_cvt_pk_bf16_f32 v0, v0, v1
	v_cvt_pk_bf16_f32 v1, v2, v3
	global_store_dwordx2 v[6:7], v[4:5], off
	global_store_dwordx2 v[6:7], v[0:1], off offset:32
	s_cbranch_vccz .LBB0_908
